# mla_norm team pass: norm weights loaded once, next row's RAW loads issued one iteration ahead
# speedup vs baseline: 1.0153x; 1.0029x over previous
.LBB0_836:
	s_cmp_eq_u32 s78, 1
	s_cbranch_scc1 P8F_ENTRY
	v_cmp_lt_i32_e32 vcc, s16, v6
	s_and_saveexec_b64 s[12:13], vcc
	s_xor_b64 s[12:13], exec, s[12:13]
	s_cbranch_execz .LBB0_838
	v_add_u32_e32 v30, 0xffffd000, v6
	v_mov_b32_e32 v31, v9
	v_lshlrev_b64 v[2:3], 10, v[30:31]
	v_lshl_add_u64 v[2:3], v[10:11], 0, v[2:3]
	global_load_dwordx4 v[2:5], v[2:3], off nt
	v_lshrrev_b32_e32 v7, 8, v30
	v_mul_u32_u24_e32 v7, 0x900, v7
	v_and_or_b32 v7, v6, s17, v7
	v_mov_b32_e32 v33, v9
	v_add_u32_e32 v32, 0x1000, v7
	v_lshlrev_b64 v[42:43], 9, v[32:33]
	v_lshlrev_b64 v[30:31], 8, v[30:31]
	v_lshl_add_u64 v[42:43], v[12:13], 0, v[42:43]
	v_lshl_add_u64 v[30:31], v[14:15], 0, v[30:31]
	s_waitcnt vmcnt(0)
	v_cvt_pk_bf16_f32 v2, v2, v3
	v_cvt_pk_bf16_f32 v3, v4, v5
	global_store_dwordx2 v[42:43], v[2:3], off
	global_load_dword v4, v[30:31], off
	v_lshlrev_b64 v[2:3], 7, v[32:33]
	v_lshl_add_u64 v[2:3], v[16:17], 0, v[2:3]
	s_waitcnt vmcnt(0)
	v_cvt_pk_bf16_f32 v4, v4, s0
	global_store_short v[2:3], v4, off

P8F_ENTRY:
	global_load_dwordx4 v[200:203], v[18:19], off
	global_load_dwordx4 v[204:207], v[18:19], off offset:16
	global_load_dwordx4 v[208:211], v[22:23], off
	v_mov_b32_e32 v244, v26
	v_mov_b32_e32 v245, 0
	v_mov_b64_e32 v[238:239], s[6:7]
	v_mad_i64_i32 v[240:241], s[84:85], v6, s18, v[238:239]
	v_lshl_add_u64 v[242:243], v[240:241], 0, v[8:9]
	global_load_dwordx4 v[2:5], v[242:243], off nt
	global_load_dwordx4 v[42:45], v[242:243], off offset:16 nt
	v_lshl_add_u64 v[240:241], v[240:241], 0, v[244:245]
	global_load_dwordx4 v[46:49], v[240:241], off offset:2048 nt
	s_mov_b32 s79, 0
P8F_LOOP:
	s_cmp_lt_u32 s79, 5
	s_cbranch_scc0 P8F_LAST
	v_add_u32_e32 v236, 4, v6
	v_mov_b64_e32 v[238:239], s[6:7]
	v_mad_i64_i32 v[240:241], s[84:85], v236, s18, v[238:239]
	v_lshl_add_u64 v[242:243], v[240:241], 0, v[8:9]
	global_load_dwordx4 v[224:227], v[242:243], off nt
	global_load_dwordx4 v[228:231], v[242:243], off offset:16 nt
	v_lshl_add_u64 v[240:241], v[240:241], 0, v[244:245]
	global_load_dwordx4 v[232:235], v[240:241], off offset:2048 nt
	s_cmp_lg_u32 s79, 0
	s_cbranch_scc1 P8F_BODY
	s_waitcnt vmcnt(3)
P8F_LAST:
P8F_BODY:
	v_cmp_lt_i32_e32 vcc, v36, v35
	v_mul_f32_e32 v30, v3, v3
	v_pk_fma_f32 v[30:31], v[2:3], v[2:3], v[30:31] op_sel_hi:[1,1,0]
	v_mul_f32_e32 v32, v5, v5
	v_pk_fma_f32 v[30:31], v[4:5], v[4:5], v[30:31]
	v_pk_mul_f32 v[60:61], v[42:43], v[42:43]
	v_pk_add_f32 v[30:31], v[32:33], v[30:31] op_sel_hi:[0,1]
	v_pk_mul_f32 v[64:65], v[46:47], v[46:47]
	v_pk_fma_f32 v[30:31], v[42:43], v[42:43], v[30:31]
	v_pk_mul_f32 v[58:59], v[44:45], v[44:45]
	v_pk_mul_f32 v[62:63], v[48:49], v[48:49]
	v_mov_b32_e32 v60, v64
	v_pk_mov_b32 v[30:31], v[64:65], v[30:31] op_sel:[1,0]
	v_mov_b32_e32 v66, v62
	v_mov_b32_e32 v67, v58
	v_pk_add_f32 v[30:31], v[60:61], v[30:31]
	v_cndmask_b32_e32 v7, v34, v36, vcc
	v_mov_b32_e32 v58, v63
	v_pk_add_f32 v[30:31], v[66:67], v[30:31]
	v_lshlrev_b32_e32 v7, 2, v7
	v_pk_add_f32 v[30:31], v[58:59], v[30:31]
	ds_bpermute_b32 v33, v7, v31
	ds_bpermute_b32 v32, v7, v30
	v_cmp_lt_i32_e32 vcc, v37, v35
	s_waitcnt lgkmcnt(0)
	v_pk_add_f32 v[30:31], v[30:31], v[32:33]
	v_cndmask_b32_e32 v7, v34, v37, vcc
	v_lshlrev_b32_e32 v7, 2, v7
	ds_bpermute_b32 v33, v7, v31
	ds_bpermute_b32 v32, v7, v30
	v_cmp_lt_i32_e32 vcc, v38, v35
	s_waitcnt lgkmcnt(0)
	v_pk_add_f32 v[30:31], v[30:31], v[32:33]
	v_cndmask_b32_e32 v7, v34, v38, vcc
	v_lshlrev_b32_e32 v7, 2, v7
	ds_bpermute_b32 v33, v7, v31
	ds_bpermute_b32 v32, v7, v30
	v_cmp_lt_i32_e32 vcc, v39, v35
	s_waitcnt lgkmcnt(0)
	v_pk_add_f32 v[30:31], v[30:31], v[32:33]
	v_cndmask_b32_e32 v7, v34, v39, vcc
	v_lshlrev_b32_e32 v7, 2, v7
	ds_bpermute_b32 v33, v7, v31
	ds_bpermute_b32 v32, v7, v30
	v_cmp_lt_i32_e32 vcc, v40, v35
	s_waitcnt lgkmcnt(0)
	v_pk_add_f32 v[30:31], v[30:31], v[32:33]
	v_cndmask_b32_e32 v7, v34, v40, vcc
	v_lshlrev_b32_e32 v7, 2, v7
	ds_bpermute_b32 v33, v7, v31
	ds_bpermute_b32 v32, v7, v30
	v_cmp_lt_i32_e32 vcc, v41, v35
	s_waitcnt lgkmcnt(0)
	v_pk_add_f32 v[30:31], v[30:31], v[32:33]
	v_cndmask_b32_e32 v7, v34, v41, vcc
	v_lshlrev_b32_e32 v7, 2, v7
	ds_bpermute_b32 v33, v7, v31
	ds_bpermute_b32 v32, v7, v30
	s_waitcnt lgkmcnt(0)
	v_pk_add_f32 v[30:31], v[30:31], v[32:33]
	s_nop 0
	v_pk_fma_f32 v[32:33], v[30:31], s[10:11], v[28:29] op_sel_hi:[1,1,0]
	s_nop 0
	v_mul_f32_e32 v7, 0x4b800000, v33
	v_cmp_gt_f32_e32 vcc, s19, v33
	s_nop 1
	v_cndmask_b32_e32 v7, v33, v7, vcc
	v_rsq_f32_e32 v27, v7
	v_ashrrev_i32_e32 v7, 31, v6
	v_lshlrev_b64 v[30:31], 10, v[6:7]
	v_lshl_add_u64 v[58:59], v[20:21], 0, v[30:31]
	v_mul_f32_e32 v33, 0x45800000, v27
	v_cndmask_b32_e32 v60, v27, v33, vcc
	v_pk_mul_f32 v[2:3], v[2:3], v[60:61] op_sel_hi:[1,0]
	v_pk_mul_f32 v[4:5], v[4:5], v[60:61] op_sel_hi:[1,0]
	v_pk_mul_f32 v[42:43], v[42:43], v[60:61] op_sel_hi:[1,0]
	v_pk_mul_f32 v[44:45], v[44:45], v[60:61] op_sel_hi:[1,0]
	v_pk_mul_f32 v[2:3], v[200:201], v[2:3]
	v_pk_mul_f32 v[4:5], v[202:203], v[4:5]
	v_pk_mul_f32 v[42:43], v[204:205], v[42:43]
	v_pk_mul_f32 v[44:45], v[44:45], v[206:207]
	v_cvt_pk_bf16_f32 v2, v2, v3
	v_cvt_pk_bf16_f32 v3, v4, v5
	v_cvt_pk_bf16_f32 v4, v42, v43
	v_cvt_pk_bf16_f32 v5, v44, v45
	global_store_dwordx4 v[58:59], v[2:5], off
	v_mul_f32_e32 v27, 0x4b800000, v32
	v_cmp_gt_f32_e32 vcc, s19, v32
	s_nop 1
	v_cndmask_b32_e32 v27, v32, v27, vcc
	v_rsq_f32_e32 v27, v27
	s_nop 0
	v_mul_f32_e32 v32, 0x45800000, v27
	v_cndmask_b32_e32 v32, v27, v32, vcc
	v_pk_mul_f32 v[42:43], v[46:47], v[32:33] op_sel_hi:[1,0]
	v_pk_mul_f32 v[32:33], v[48:49], v[32:33] op_sel_hi:[1,0]
	v_cmp_lt_i32_e32 vcc, s24, v6
	v_pk_mul_f32 v[2:3], v[42:43], v[208:209]
	v_pk_mul_f32 v[4:5], v[32:33], v[210:211]
	v_cvt_pk_bf16_f32 v32, v2, v3
	v_cvt_pk_bf16_f32 v33, v4, v5
	s_and_saveexec_b64 s[14:15], vcc
	s_xor_b64 s[14:15], exec, s[14:15]
	s_cbranch_execz P8F_841
	v_add_u32_e32 v2, 0xfffff000, v6
	v_lshrrev_b32_e32 v2, 11, v2
	v_mul_u32_u24_e32 v2, 0x900, v2
	v_and_b32_e32 v3, 0x7ff, v6
	v_add3_u32 v2, v3, v2, s25
	v_mov_b32_e32 v3, v9
	v_lshlrev_b64 v[2:3], 9, v[2:3]
	v_lshl_add_u64 v[2:3], v[12:13], 0, v[2:3]
	global_store_dwordx2 v[2:3], v[32:33], off
P8F_841:
	s_andn2_saveexec_b64 s[14:15], s[14:15]
	s_cbranch_execz P8F_834
	v_lshlrev_b64 v[42:43], 9, v[6:7]
	v_lshl_add_u64 v[42:43], v[12:13], 0, v[42:43]
	v_lshl_add_u64 v[30:31], v[24:25], 0, v[30:31]
	global_store_dwordx2 v[42:43], v[32:33], off
	global_store_dwordx4 v[30:31], v[2:5], off nt
	s_branch P8F_834
P8F_834:
	s_or_b64 exec, exec, s[14:15]
	s_add_u32 s79, s79, 1
	s_cmp_lt_u32 s79, 6
	s_cbranch_scc0 .LBB0_843
	v_add_u32_e32 v6, 4, v6
	s_waitcnt vmcnt(2)
	v_mov_b32_e32 v2, v224
	v_mov_b32_e32 v3, v225
	v_mov_b32_e32 v4, v226
	v_mov_b32_e32 v5, v227
	v_mov_b32_e32 v42, v228
	v_mov_b32_e32 v43, v229
	v_mov_b32_e32 v44, v230
	v_mov_b32_e32 v45, v231
	v_mov_b32_e32 v46, v232
	v_mov_b32_e32 v47, v233
	v_mov_b32_e32 v48, v234
	v_mov_b32_e32 v49, v235
	s_branch P8F_LOOP
